# static priority level 3 (instead of 1) for the staggered wave half at each GEMM phase entry
# baseline (speedup 1.0000x reference)
; #define PG8_STAGE(bufoff, gbase, voff) do { _Pragma("unroll") for (int _i = 0; _i < 2; ++_i) \
;         __builtin_amdgcn_global_load_lds((const unsigned*)((const char*)(gbase) + (voff)[_i]), (PG8_LAS unsigned*)(lds + (bufoff) + ldsw + _i * 8192), 16, 0, 0); } while (0)
; #define PG8_BAR __builtin_amdgcn_s_barrier()
;     __host__ __device__ bool next(int i, Unit& u) const {
;         const long L = (long)i * G + c; if (L >= nwg) return false;
;         int wgid = (int)L; { const int q = nwg / NXCD, r = nwg % NXCD, xcd = wgid % NXCD, off = wgid / NXCD; wgid = (xcd < r ? xcd * (q + 1) : r * (q + 1) + (xcd - r) * q) + off; }
;         const int nig = WGM * nN, gid = wgid / nig, fm = gid * WGM, gsz = (nM - fm) < WGM ? (nM - fm) : WGM;
;         u.pm = fm + ((wgid % nig) % gsz); u.pn = (wgid % nig) / gsz; return true;
; template <class Epi, class Sched, bool ALIGN_EPI = false, bool SP2 = false>
; __device__ __forceinline__ void gemm_phase(PG8_LAS unsigned char* lds, const Gemm g, const Sched& S, const Epi& E) {
;     ...
;     for (int i = 0; i < 2; ++i) { int R, C; stage_rc(tid * 16 + i * 8192, R, C); const int Rb = Epi::PERM ? ((R & ~31) + perm32(R & 31)) : R;
;         voffA[i] = (unsigned)(R * g.lda + C) * 2u; voffB[i] = (unsigned)(Rb * g.ldb + C) * 2u; }
;     const size_t kstep = (size_t)(BK * 2);
;     const size_t hstepA = (size_t)HALF * g.lda * 2, hstepB = (size_t)HALF * g.ldb * 2;
;     const size_t tstepA = 2 * hstepA, tstepB = 2 * hstepB;
;     const unsigned ldsw = (unsigned)wid * 1024u;
;     const int aoff = lds_byte(wr * 64 + fr, fq * 8), boff = lds_byte(wc * 32 + fr, fq * 8);
;     ...
;     Unit cur, nxt; int ui = 0;
;     if (!S.next(0, cur)) return;
;     f32x4 acc[2][2][4][2];
; #pragma unroll
;     for (int a = 0; a < 2; ++a)
; #pragma unroll
;         for (int b = 0; b < 2; ++b)
; #pragma unroll
;             for (int m = 0; m < 4; ++m)
; #pragma unroll
;                 for (int n = 0; n < 2; ++n) acc[a][b][m][n] = (f32x4){0.f, 0.f, 0.f, 0.f};
;     bf16x8 At[4][2], B0[2][2], B1[2][2];
;     const char* cA = PG8_ABASE(cur); const char* cB = (const char*)g.Bt + (size_t)cur.pn * tstepB;
;     S.a_ready(cur);
;     if constexpr (SP2) {
;         PG8_STAGE(PG8_SB(0, 0), cB, voffB); PG8_STAGE(PG8_SB(0, 1), cB + hstepB, voffB); PG8_STAGE(PG8_SA(0, 0), cA, voffA); PG8_STAGE(PG8_SA(0, 1), cA + hstepA, voffA);
;         if (wr == 1) PG8_BAR;
.LBB0_135:
	v_lshrrev_b32_e32 v4, 1, v0
	v_and_b32_e32 v14, 24, v4
	v_lshrrev_b32_e32 v4, 5, v0
	v_lshlrev_b32_e32 v2, 4, v0
	v_and_b32_e32 v3, 32, v0
	v_and_b32_e32 v4, 4, v4
	v_bfe_u32 v5, v0, 2, 2
	v_bfe_u32 v12, v0, 2, 4
	v_bitop3_b32 v10, v2, v3, 48 bitop3:0x6c
	v_and_b32_e32 v11, 64, v0
	v_or3_b32 v4, v4, v5, v14
	v_lshrrev_b32_e32 v5, 3, v0
	v_or_b32_e32 v13, 0x2000, v2
	v_or_b32_e32 v3, v10, v11
	v_and_or_b32 v6, v5, 48, v12
	v_and_or_b32 v5, v5, 32, v4
	v_lshrrev_b32_e32 v2, 7, v13
	s_movk_i32 s1, 0x70
	v_lshl_or_b32 v140, v5, 13, v3
	v_and_or_b32 v5, v2, s1, v12
	s_movk_i32 s1, 0x60
	v_and_or_b32 v2, v2, s1, v4
	s_lshr_b32 s5, s14, 6
	s_ashr_i32 s1, s0, 31
	s_ashr_i32 s55, s54, 31
	s_lshr_b32 s4, s14, 8
	s_lshl_b32 s66, s5, 10
	s_lshl_b64 s[6:7], s[0:1], 21
	s_lshl_b64 s[8:9], s[54:55], 21
	s_add_u32 s8, s12, s8
	s_addc_u32 s9, s13, s9
	s_add_i32 s55, s66, 0
	s_add_i32 m0, s55, 0x10000
	v_lshl_or_b32 v144, v2, 13, v3
	global_load_lds_dwordx4 v140, s[8:9]
	s_add_i32 m0, s55, 0x12000
	s_add_u32 s16, s8, 0x100000
	global_load_lds_dwordx4 v144, s[8:9]
	s_addc_u32 s17, s9, 0
	s_add_i32 m0, s55, 0x14000
	v_lshl_or_b32 v138, v6, 13, v3
	global_load_lds_dwordx4 v140, s[16:17]
	s_add_i32 m0, s55, 0x16000
	s_add_u32 s6, s38, s6
	s_addc_u32 s7, s39, s7
	s_add_i32 s67, s55, 0x2000
	global_load_lds_dwordx4 v144, s[16:17]
	s_mov_b32 m0, s55
	s_add_u32 s16, s6, 0x100000
	v_lshl_or_b32 v142, v5, 13, v3
	global_load_lds_dwordx4 v138, s[6:7]
	s_mov_b32 m0, s67
	s_addc_u32 s17, s7, 0
	s_add_i32 s72, s55, 0x4000
	global_load_lds_dwordx4 v142, s[6:7]
	s_mov_b32 m0, s72
	s_add_i32 s73, s55, 0x6000
	global_load_lds_dwordx4 v138, s[16:17]
	s_mov_b32 m0, s73
	v_mov_b32_e32 v147, 0
	global_load_lds_dwordx4 v142, s[16:17]
	v_mov_b32_e32 v141, v147
	v_mov_b32_e32 v145, v147
	v_mov_b32_e32 v139, v147
	v_mov_b32_e32 v143, v147
	s_cmp_eq_u32 s4, 1
	s_mov_b32 s84, s89
	s_mov_b64 s[78:79], s[90:91]
	s_mov_b32 s15, 0
	v_lshl_add_u64 v[8:9], s[8:9], 0, v[140:141]
	v_lshl_add_u64 v[4:5], s[8:9], 0, v[144:145]
	v_lshl_add_u64 v[2:3], s[6:7], 0, v[138:139]
	s_cselect_b64 s[16:17], -1, 0
	s_cmp_lg_u32 s4, 1
	v_lshl_add_u64 v[6:7], s[6:7], 0, v[142:143]
	s_cbranch_scc1 .LBB0_137
	s_barrier
	s_setprio 3

; #define PG8_STAGE(bufoff, gbase, voff) do { _Pragma("unroll") for (int _i = 0; _i < 2; ++_i) \
;         __builtin_amdgcn_global_load_lds((const unsigned*)((const char*)(gbase) + (voff)[_i]), (PG8_LAS unsigned*)(lds + (bufoff) + ldsw + _i * 8192), 16, 0, 0); } while (0)
; #define PG8_BAR __builtin_amdgcn_s_barrier()
;     __host__ __device__ bool next(int i, Unit& u) const {
;         const long L = (long)i * G + c; if (L >= nwg) return false;
;         int wgid = (int)L; { const int q = nwg / NXCD, r = nwg % NXCD, xcd = wgid % NXCD, off = wgid / NXCD; wgid = (xcd < r ? xcd * (q + 1) : r * (q + 1) + (xcd - r) * q) + off; }
;         const int nig = WGM * nN, gid = wgid / nig, fm = gid * WGM, gsz = (nM - fm) < WGM ? (nM - fm) : WGM;
;         u.pm = fm + ((wgid % nig) % gsz); u.pn = (wgid % nig) / gsz; return true;
; template <class Epi, class Sched, bool ALIGN_EPI = false, bool SP2 = false>
; __device__ __forceinline__ void gemm_phase(PG8_LAS unsigned char* lds, const Gemm g, const Sched& S, const Epi& E) {
;     ...
;     for (int i = 0; i < 2; ++i) { int R, C; stage_rc(tid * 16 + i * 8192, R, C); const int Rb = Epi::PERM ? ((R & ~31) + perm32(R & 31)) : R;
;         voffA[i] = (unsigned)(R * g.lda + C) * 2u; voffB[i] = (unsigned)(Rb * g.ldb + C) * 2u; }
;     const size_t kstep = (size_t)(BK * 2);
;     const size_t hstepA = (size_t)HALF * g.lda * 2, hstepB = (size_t)HALF * g.ldb * 2;
;     const size_t tstepA = 2 * hstepA, tstepB = 2 * hstepB;
;     const unsigned ldsw = (unsigned)wid * 1024u;
;     const int aoff = lds_byte(wr * 64 + fr, fq * 8), boff = lds_byte(wc * 32 + fr, fq * 8);
;     ...
;     Unit cur, nxt; int ui = 0;
;     if (!S.next(0, cur)) return;
;     f32x4 acc[2][2][4][2];
; #pragma unroll
;     for (int a = 0; a < 2; ++a)
; #pragma unroll
;         for (int b = 0; b < 2; ++b)
; #pragma unroll
;             for (int m = 0; m < 4; ++m)
; #pragma unroll
;                 for (int n = 0; n < 2; ++n) acc[a][b][m][n] = (f32x4){0.f, 0.f, 0.f, 0.f};
;     bf16x8 At[4][2], B0[2][2], B1[2][2];
;     const char* cA = PG8_ABASE(cur); const char* cB = (const char*)g.Bt + (size_t)cur.pn * tstepB;
;     S.a_ready(cur);
;     if constexpr (SP2) {
;         PG8_STAGE(PG8_SB(0, 0), cB, voffB); PG8_STAGE(PG8_SB(0, 1), cB + hstepB, voffB); PG8_STAGE(PG8_SA(0, 0), cA, voffA); PG8_STAGE(PG8_SA(0, 1), cA + hstepA, voffA);
;         if (wr == 1) PG8_BAR;
.LBB0_464:
	v_lshrrev_b32_e32 v4, 1, v0
	v_and_b32_e32 v13, 24, v4
	v_lshrrev_b32_e32 v4, 5, v0
	v_lshlrev_b32_e32 v2, 4, v0
	v_and_b32_e32 v3, 32, v0
	v_and_b32_e32 v4, 4, v4
	v_bfe_u32 v5, v0, 2, 2
	v_bfe_u32 v12, v0, 2, 4
	v_bitop3_b32 v10, v2, v3, 48 bitop3:0x6c
	v_and_b32_e32 v11, 64, v0
	v_or3_b32 v4, v4, v5, v13
	v_lshrrev_b32_e32 v5, 3, v0
	v_or_b32_e32 v14, 0x2000, v2
	s_ashr_i32 s0, s5, 3
	v_or_b32_e32 v3, v10, v11
	v_and_or_b32 v6, v5, 48, v12
	v_and_or_b32 v5, v5, 32, v4
	v_lshrrev_b32_e32 v2, 7, v14
	s_movk_i32 s1, 0x70
	v_lshl_or_b32 v148, v5, 10, v3
	v_and_or_b32 v5, v2, s1, v12
	s_movk_i32 s1, 0x60
	s_add_i32 s0, s7, s0
	v_and_or_b32 v2, v2, s1, v4
	s_ashr_i32 s1, s0, 31
	s_lshr_b32 s1, s1, 26
	s_add_i32 s1, s0, s1
	s_ashr_i32 s7, s1, 6
	s_andn2_b32 s1, s1, 63
	s_sub_i32 s1, s0, s1
	s_bfe_i32 s0, s1, 0x80000
	s_bfe_u32 s0, s0, 0x3000c
	s_add_i32 s18, s1, s0
	s_bfe_i32 s0, s18, 0x80000
	s_and_b32 s18, s18, 0xf8
	s_sext_i32_i16 s19, s0
	s_sub_i32 s1, s1, s18
	s_lshl_b32 s7, s7, 3
	s_sext_i32_i8 s1, s1
	s_ashr_i32 s76, s19, 3
	s_add_i32 s30, s7, s1
	s_lshl_b32 s1, s76, 8
	s_lshr_b32 s0, s19, 3
	s_and_b32 s20, s1, 0xfffffe00
	s_lshr_b32 s6, s4, 6
	s_ashr_i32 s31, s30, 31
	s_ashr_i32 s21, s20, 31
	s_bfe_i64 s[0:1], s[0:1], 0x100000
	s_lshr_b32 s5, s4, 8
	s_lshl_b32 s44, s6, 10
	s_lshl_b64 s[18:19], s[30:31], 20
	s_lshl_b64 s[20:21], s[20:21], 1
	s_lshl_b64 s[0:1], s[0:1], 18
	s_add_u32 s36, s10, s0
	s_addc_u32 s37, s11, s1
	s_add_i32 s31, s44, 0
	s_add_i32 m0, s31, 0x10000
	v_lshl_or_b32 v152, v2, 10, v3
	global_load_lds_dwordx4 v148, s[36:37]
	s_add_i32 m0, s31, 0x12000
	s_add_u32 s7, s16, s18
	s_addc_u32 s18, s17, s19
	s_add_u32 s0, s36, 0x20000
	global_load_lds_dwordx4 v152, s[36:37]
	s_addc_u32 s1, s37, 0
	s_add_i32 m0, s31, 0x14000
	v_lshl_or_b32 v146, v6, 12, v3
	global_load_lds_dwordx4 v148, s[0:1]
	s_add_i32 m0, s31, 0x16000
	s_add_u32 s58, s7, s20
	s_addc_u32 s59, s18, s21
	s_add_i32 s45, s31, 0x2000
	global_load_lds_dwordx4 v152, s[0:1]
	s_mov_b32 m0, s31
	s_add_u32 s0, s58, 0x80000
	v_lshl_or_b32 v150, v5, 12, v3
	global_load_lds_dwordx4 v146, s[58:59]
	s_mov_b32 m0, s45
	s_addc_u32 s1, s59, 0
	s_add_i32 s54, s31, 0x4000
	global_load_lds_dwordx4 v150, s[58:59]
	s_mov_b32 m0, s54
	s_add_i32 s55, s31, 0x6000
	global_load_lds_dwordx4 v146, s[0:1]
	s_mov_b32 m0, s55
	v_mov_b32_e32 v149, 0
	global_load_lds_dwordx4 v150, s[0:1]
	v_mov_b32_e32 v153, v149
	v_mov_b32_e32 v147, v149
	v_mov_b32_e32 v151, v149
	s_cmp_eq_u32 s5, 1
	s_mov_b32 s62, 0
	v_lshl_add_u64 v[8:9], s[36:37], 0, v[148:149]
	v_lshl_add_u64 v[6:7], s[36:37], 0, v[152:153]
	v_lshl_add_u64 v[2:3], s[58:59], 0, v[146:147]
	s_cselect_b64 s[0:1], -1, 0
	s_cmp_lg_u32 s5, 1
	v_lshl_add_u64 v[4:5], s[58:59], 0, v[150:151]
	s_cbranch_scc1 .LBB0_466
	s_barrier
	s_setprio 3

; #define PG8_STAGE(bufoff, gbase, voff) do { _Pragma("unroll") for (int _i = 0; _i < 2; ++_i) \
;         __builtin_amdgcn_global_load_lds((const unsigned*)((const char*)(gbase) + (voff)[_i]), (PG8_LAS unsigned*)(lds + (bufoff) + ldsw + _i * 8192), 16, 0, 0); } while (0)
; #define PG8_BAR __builtin_amdgcn_s_barrier()
;     __host__ __device__ bool next(int i, Unit& u) const {
;         const long L = (long)i * G + c; if (L >= nwg) return false;
;         int wgid = (int)L; { const int q = nwg / NXCD, r = nwg % NXCD, xcd = wgid % NXCD, off = wgid / NXCD; wgid = (xcd < r ? xcd * (q + 1) : r * (q + 1) + (xcd - r) * q) + off; }
;         const int nig = WGM * nN, gid = wgid / nig, fm = gid * WGM, gsz = (nM - fm) < WGM ? (nM - fm) : WGM;
;         u.pm = fm + ((wgid % nig) % gsz); u.pn = (wgid % nig) / gsz; return true;
; template <class Epi, class Sched, bool ALIGN_EPI = false, bool SP2 = false>
; __device__ __forceinline__ void gemm_phase(PG8_LAS unsigned char* lds, const Gemm g, const Sched& S, const Epi& E) {
;     ...
;     for (int i = 0; i < 2; ++i) { int R, C; stage_rc(tid * 16 + i * 8192, R, C); const int Rb = Epi::PERM ? ((R & ~31) + perm32(R & 31)) : R;
;         voffA[i] = (unsigned)(R * g.lda + C) * 2u; voffB[i] = (unsigned)(Rb * g.ldb + C) * 2u; }
;     const size_t kstep = (size_t)(BK * 2);
;     const size_t hstepA = (size_t)HALF * g.lda * 2, hstepB = (size_t)HALF * g.ldb * 2;
;     const size_t tstepA = 2 * hstepA, tstepB = 2 * hstepB;
;     const unsigned ldsw = (unsigned)wid * 1024u;
;     const int aoff = lds_byte(wr * 64 + fr, fq * 8), boff = lds_byte(wc * 32 + fr, fq * 8);
;     ...
;     Unit cur, nxt; int ui = 0;
;     if (!S.next(0, cur)) return;
;     f32x4 acc[2][2][4][2];
; #pragma unroll
;     for (int a = 0; a < 2; ++a)
; #pragma unroll
;         for (int b = 0; b < 2; ++b)
; #pragma unroll
;             for (int m = 0; m < 4; ++m)
; #pragma unroll
;                 for (int n = 0; n < 2; ++n) acc[a][b][m][n] = (f32x4){0.f, 0.f, 0.f, 0.f};
;     bf16x8 At[4][2], B0[2][2], B1[2][2];
;     const char* cA = PG8_ABASE(cur); const char* cB = (const char*)g.Bt + (size_t)cur.pn * tstepB;
;     S.a_ready(cur);
;     if constexpr (SP2) {
;         PG8_STAGE(PG8_SB(0, 0), cB, voffB); PG8_STAGE(PG8_SB(0, 1), cB + hstepB, voffB); PG8_STAGE(PG8_SA(0, 0), cA, voffA); PG8_STAGE(PG8_SA(0, 1), cA + hstepA, voffA);
;         if (wr == 1) PG8_BAR;
.LBB0_715:
	v_lshrrev_b32_e32 v4, 1, v0
	v_lshrrev_b32_e32 v5, 5, v0
	v_lshlrev_b32_e32 v2, 4, v0
	v_and_b32_e32 v3, 32, v0
	v_and_b32_e32 v4, 24, v4
	v_and_b32_e32 v5, 4, v5
	v_bfe_u32 v6, v0, 2, 2
	s_waitcnt vmcnt(0)
	v_bfe_u32 v12, v0, 2, 4
	v_bitop3_b32 v10, v2, v3, 48 bitop3:0x6c
	v_and_b32_e32 v11, 64, v0
	v_or3_b32 v4, v5, v6, v4
	v_lshrrev_b32_e32 v5, 3, v0
	v_or_b32_e32 v13, 0x2000, v2
	s_ashr_i32 s0, s6, 3
	v_or_b32_e32 v3, v10, v11
	v_and_or_b32 v6, v5, 48, v12
	v_and_or_b32 v5, v5, 32, v4
	v_lshrrev_b32_e32 v2, 7, v13
	s_movk_i32 s1, 0x70
	v_lshl_or_b32 v136, v5, 13, v3
	v_and_or_b32 v5, v2, s1, v12
	s_movk_i32 s1, 0x60
	s_add_i32 s0, s4, s0
	v_and_or_b32 v2, v2, s1, v4
	s_ashr_i32 s1, s0, 31
	s_lshr_b32 s1, s1, 25
	s_add_i32 s1, s0, s1
	s_ashr_i32 s4, s1, 7
	s_and_b32 s1, s1, 0xffffff80
	s_sub_i32 s0, s0, s1
	s_bfe_i32 s1, s0, 0x80000
	s_bfe_u32 s1, s1, 0x3000c
	s_add_i32 s1, s0, s1
	s_lshl_b32 s6, s4, 3
	s_bfe_i32 s4, s1, 0x80000
	s_and_b32 s1, s1, 0xf8
	s_sub_i32 s0, s0, s1
	s_sext_i32_i16 s4, s4
	s_sext_i32_i8 s0, s0
	s_lshr_b32 s4, s4, 3
	s_add_i32 s0, s6, s0
	s_lshr_b32 s11, s5, 6
	s_ashr_i32 s1, s0, 31
	s_bfe_i64 s[8:9], s[4:5], 0x100000
	s_lshr_b32 s10, s5, 8
	s_lshl_b32 s33, s11, 10
	s_lshl_b64 s[6:7], s[0:1], 21
	s_lshl_b64 s[8:9], s[8:9], 21
	v_readlane_b32 s12, v244, 2
	v_readlane_b32 s13, v244, 3
	s_add_u32 s30, s12, s8
	s_addc_u32 s31, s13, s9
	s_add_i32 s44, s33, 0
	s_add_i32 m0, s44, 0x10000
	v_lshl_or_b32 v140, v2, 13, v3
	global_load_lds_dwordx4 v136, s[30:31]
	s_add_i32 m0, s44, 0x12000
	s_add_u32 s8, s30, 0x100000
	global_load_lds_dwordx4 v140, s[30:31]
	s_addc_u32 s9, s31, 0
	s_add_i32 m0, s44, 0x14000
	v_lshl_or_b32 v134, v6, 13, v3
	global_load_lds_dwordx4 v136, s[8:9]
	s_add_i32 m0, s44, 0x16000
	s_add_u32 s28, s56, s6
	s_addc_u32 s29, s57, s7
	s_add_i32 s45, s44, 0x2000
	global_load_lds_dwordx4 v140, s[8:9]
	s_mov_b32 m0, s44
	s_add_u32 s6, s28, 0x100000
	v_lshl_or_b32 v138, v5, 13, v3
	global_load_lds_dwordx4 v134, s[28:29]
	s_mov_b32 m0, s45
	s_addc_u32 s7, s29, 0
	s_add_i32 s54, s44, 0x4000
	global_load_lds_dwordx4 v138, s[28:29]
	s_mov_b32 m0, s54
	s_add_i32 s55, s44, 0x6000
	global_load_lds_dwordx4 v134, s[6:7]
	s_mov_b32 m0, s55
	v_mov_b32_e32 v137, 0
	global_load_lds_dwordx4 v138, s[6:7]
	v_mov_b32_e32 v141, v137
	v_mov_b32_e32 v135, v137
	v_mov_b32_e32 v139, v137
	s_cmp_eq_u32 s10, 1
	s_mov_b32 s58, 0
	v_lshl_add_u64 v[8:9], s[30:31], 0, v[136:137]
	v_lshl_add_u64 v[4:5], s[30:31], 0, v[140:141]
	s_mov_b64 s[6:7], 0x100000
	v_lshl_add_u64 v[2:3], s[28:29], 0, v[134:135]
	s_cselect_b64 s[8:9], -1, 0
	s_cmp_lg_u32 s10, 1
	v_lshl_add_u64 v[6:7], s[28:29], 0, v[138:139]
	s_cbranch_scc1 .LBB0_717
	s_barrier
	s_setprio 3

; #define PG8_STAGE(bufoff, gbase, voff) do { _Pragma("unroll") for (int _i = 0; _i < 2; ++_i) \
;         __builtin_amdgcn_global_load_lds((const unsigned*)((const char*)(gbase) + (voff)[_i]), (PG8_LAS unsigned*)(lds + (bufoff) + ldsw + _i * 8192), 16, 0, 0); } while (0)
; #define PG8_BAR __builtin_amdgcn_s_barrier()
;     __host__ __device__ bool next(int i, Unit& u) const {
;         const long L = (long)i * G + c; if (L >= nwg) return false;
;         int wgid = (int)L; { const int q = nwg / NXCD, r = nwg % NXCD, xcd = wgid % NXCD, off = wgid / NXCD; wgid = (xcd < r ? xcd * (q + 1) : r * (q + 1) + (xcd - r) * q) + off; }
;         const int nig = WGM * nN, gid = wgid / nig, fm = gid * WGM, gsz = (nM - fm) < WGM ? (nM - fm) : WGM;
;         u.pm = fm + ((wgid % nig) % gsz); u.pn = (wgid % nig) / gsz; return true;
; template <class Epi, class Sched, bool ALIGN_EPI = false, bool SP2 = false>
; __device__ __forceinline__ void gemm_phase(PG8_LAS unsigned char* lds, const Gemm g, const Sched& S, const Epi& E) {
;     ...
;     for (int i = 0; i < 2; ++i) { int R, C; stage_rc(tid * 16 + i * 8192, R, C); const int Rb = Epi::PERM ? ((R & ~31) + perm32(R & 31)) : R;
;         voffA[i] = (unsigned)(R * g.lda + C) * 2u; voffB[i] = (unsigned)(Rb * g.ldb + C) * 2u; }
;     const size_t kstep = (size_t)(BK * 2);
;     const size_t hstepA = (size_t)HALF * g.lda * 2, hstepB = (size_t)HALF * g.ldb * 2;
;     const size_t tstepA = 2 * hstepA, tstepB = 2 * hstepB;
;     const unsigned ldsw = (unsigned)wid * 1024u;
;     const int aoff = lds_byte(wr * 64 + fr, fq * 8), boff = lds_byte(wc * 32 + fr, fq * 8);
;     ...
;     Unit cur, nxt; int ui = 0;
;     if (!S.next(0, cur)) return;
;     f32x4 acc[2][2][4][2];
; #pragma unroll
;     for (int a = 0; a < 2; ++a)
; #pragma unroll
;         for (int b = 0; b < 2; ++b)
; #pragma unroll
;             for (int m = 0; m < 4; ++m)
; #pragma unroll
;                 for (int n = 0; n < 2; ++n) acc[a][b][m][n] = (f32x4){0.f, 0.f, 0.f, 0.f};
;     bf16x8 At[4][2], B0[2][2], B1[2][2];
;     const char* cA = PG8_ABASE(cur); const char* cB = (const char*)g.Bt + (size_t)cur.pn * tstepB;
;     S.a_ready(cur);
;     if constexpr (SP2) {
;         PG8_STAGE(PG8_SB(0, 0), cB, voffB); PG8_STAGE(PG8_SB(0, 1), cB + hstepB, voffB); PG8_STAGE(PG8_SA(0, 0), cA, voffA); PG8_STAGE(PG8_SA(0, 1), cA + hstepA, voffA);
;         if (wr == 1) PG8_BAR;
.LBB0_796:
	v_lshrrev_b32_e32 v5, 1, v0
	v_lshrrev_b32_e32 v6, 5, v0
	v_lshlrev_b32_e32 v2, 4, v0
	v_and_b32_e32 v3, 32, v0
	v_and_b32_e32 v5, 24, v5
	v_and_b32_e32 v6, 4, v6
	v_bfe_u32 v7, v0, 2, 2
	s_waitcnt vmcnt(0)
	v_bfe_u32 v13, v0, 2, 4
	v_bitop3_b32 v3, v2, v3, 48 bitop3:0x6c
	v_and_b32_e32 v12, 64, v0
	v_or3_b32 v5, v6, v7, v5
	v_lshrrev_b32_e32 v6, 3, v0
	v_or_b32_e32 v14, 0x2000, v2
	s_ashr_i32 s0, s6, 3
	v_or_b32_e32 v4, v3, v12
	v_and_or_b32 v7, v6, 48, v13
	v_and_or_b32 v6, v6, 32, v5
	v_lshrrev_b32_e32 v2, 7, v14
	s_movk_i32 s1, 0x70
	v_lshl_or_b32 v166, v6, 13, v4
	v_and_or_b32 v6, v2, s1, v13
	s_movk_i32 s1, 0x60
	s_add_i32 s0, s4, s0
	v_and_or_b32 v2, v2, s1, v5
	s_ashr_i32 s1, s0, 31
	s_lshr_b32 s1, s1, 25
	s_add_i32 s1, s0, s1
	s_ashr_i32 s4, s1, 7
	s_and_b32 s1, s1, 0xffffff80
	s_sub_i32 s0, s0, s1
	s_bfe_i32 s1, s0, 0x80000
	s_bfe_u32 s1, s1, 0x3000c
	s_add_i32 s1, s0, s1
	s_lshl_b32 s10, s4, 3
	s_bfe_i32 s4, s1, 0x80000
	s_and_b32 s1, s1, 0xf8
	s_sub_i32 s0, s0, s1
	s_sext_i32_i16 s4, s4
	s_sext_i32_i8 s0, s0
	s_lshr_b32 s4, s4, 3
	s_add_i32 s30, s10, s0
	s_lshr_b32 s6, s5, 6
	s_ashr_i32 s31, s30, 31
	s_bfe_i64 s[10:11], s[4:5], 0x100000
	s_lshr_b32 s7, s5, 8
	s_lshl_b32 s33, s6, 10
	s_lshl_b64 s[0:1], s[30:31], 21
	s_lshl_b64 s[10:11], s[10:11], 21
	v_readlane_b32 s12, v244, 4
	v_readlane_b32 s13, v244, 5
	s_add_u32 s36, s12, s10
	s_addc_u32 s37, s13, s11
	s_add_i32 s42, s33, 0
	s_add_i32 m0, s42, 0x10000
	v_lshl_or_b32 v170, v2, 13, v4
	global_load_lds_dwordx4 v166, s[36:37]
	s_add_i32 m0, s42, 0x12000
	s_add_u32 s10, s36, 0x100000
	global_load_lds_dwordx4 v170, s[36:37]
	s_addc_u32 s11, s37, 0
	s_add_i32 m0, s42, 0x14000
	v_lshl_or_b32 v164, v7, 13, v4
	global_load_lds_dwordx4 v166, s[10:11]
	s_add_i32 m0, s42, 0x16000
	s_add_u32 s28, s38, s0
	s_addc_u32 s29, s39, s1
	s_add_i32 s43, s42, 0x2000
	global_load_lds_dwordx4 v170, s[10:11]
	s_mov_b32 m0, s42
	s_add_u32 s0, s28, 0x100000
	v_lshl_or_b32 v168, v6, 13, v4
	global_load_lds_dwordx4 v164, s[28:29]
	s_mov_b32 m0, s43
	s_addc_u32 s1, s29, 0
	s_add_i32 s44, s42, 0x4000
	global_load_lds_dwordx4 v168, s[28:29]
	s_mov_b32 m0, s44
	s_add_i32 s45, s42, 0x6000
	global_load_lds_dwordx4 v164, s[0:1]
	s_mov_b32 m0, s45
	v_mov_b32_e32 v2, 0
	global_load_lds_dwordx4 v168, s[0:1]
	v_mov_b32_e32 v167, v2
	v_mov_b32_e32 v171, v2
	v_mov_b32_e32 v165, v2
	v_mov_b32_e32 v169, v2
	s_cmp_eq_u32 s7, 1
	s_mov_b32 s54, 0
	v_lshl_add_u64 v[10:11], s[36:37], 0, v[166:167]
	v_lshl_add_u64 v[6:7], s[36:37], 0, v[170:171]
	v_lshl_add_u64 v[4:5], s[28:29], 0, v[164:165]
	s_cselect_b64 s[0:1], -1, 0
	s_cmp_lg_u32 s7, 1
	v_lshl_add_u64 v[8:9], s[28:29], 0, v[168:169]
	s_cbranch_scc1 .LBB0_798
	s_barrier
	s_setprio 3

; #define PG8_STAGE(bufoff, gbase, voff) do { _Pragma("unroll") for (int _i = 0; _i < 2; ++_i) \
;         __builtin_amdgcn_global_load_lds((const unsigned*)((const char*)(gbase) + (voff)[_i]), (PG8_LAS unsigned*)(lds + (bufoff) + ldsw + _i * 8192), 16, 0, 0); } while (0)
; #define PG8_BAR __builtin_amdgcn_s_barrier()
;     __host__ __device__ bool next(int i, Unit& u) const {
;         const long L = (long)i * G + c; if (L >= nwg) return false;
;         int wgid = (int)L; { const int q = nwg / NXCD, r = nwg % NXCD, xcd = wgid % NXCD, off = wgid / NXCD; wgid = (xcd < r ? xcd * (q + 1) : r * (q + 1) + (xcd - r) * q) + off; }
;         const int nig = WGM * nN, gid = wgid / nig, fm = gid * WGM, gsz = (nM - fm) < WGM ? (nM - fm) : WGM;
;         u.pm = fm + ((wgid % nig) % gsz); u.pn = (wgid % nig) / gsz; return true;
; template <class Epi, class Sched, bool ALIGN_EPI = false, bool SP2 = false>
; __device__ __forceinline__ void gemm_phase(PG8_LAS unsigned char* lds, const Gemm g, const Sched& S, const Epi& E) {
;     ...
;     for (int i = 0; i < 2; ++i) { int R, C; stage_rc(tid * 16 + i * 8192, R, C); const int Rb = Epi::PERM ? ((R & ~31) + perm32(R & 31)) : R;
;         voffA[i] = (unsigned)(R * g.lda + C) * 2u; voffB[i] = (unsigned)(Rb * g.ldb + C) * 2u; }
;     const size_t kstep = (size_t)(BK * 2);
;     const size_t hstepA = (size_t)HALF * g.lda * 2, hstepB = (size_t)HALF * g.ldb * 2;
;     const size_t tstepA = 2 * hstepA, tstepB = 2 * hstepB;
;     const unsigned ldsw = (unsigned)wid * 1024u;
;     const int aoff = lds_byte(wr * 64 + fr, fq * 8), boff = lds_byte(wc * 32 + fr, fq * 8);
;     ...
;     Unit cur, nxt; int ui = 0;
;     if (!S.next(0, cur)) return;
;     f32x4 acc[2][2][4][2];
; #pragma unroll
;     for (int a = 0; a < 2; ++a)
; #pragma unroll
;         for (int b = 0; b < 2; ++b)
; #pragma unroll
;             for (int m = 0; m < 4; ++m)
; #pragma unroll
;                 for (int n = 0; n < 2; ++n) acc[a][b][m][n] = (f32x4){0.f, 0.f, 0.f, 0.f};
;     bf16x8 At[4][2], B0[2][2], B1[2][2];
;     const char* cA = PG8_ABASE(cur); const char* cB = (const char*)g.Bt + (size_t)cur.pn * tstepB;
;     S.a_ready(cur);
;     if constexpr (SP2) {
;         PG8_STAGE(PG8_SB(0, 0), cB, voffB); PG8_STAGE(PG8_SB(0, 1), cB + hstepB, voffB); PG8_STAGE(PG8_SA(0, 0), cA, voffA); PG8_STAGE(PG8_SA(0, 1), cA + hstepA, voffA);
;         if (wr == 1) PG8_BAR;
.LBB0_899:
	s_andn2_b64 vcc, exec, s[0:1]
	v_readfirstlane_b32 s1, v0
	s_waitcnt vmcnt(0) lgkmcnt(0)
	s_barrier
	s_cbranch_vccnz .LBB0_915
	v_lshrrev_b32_e32 v2, 5, v0
	v_lshrrev_b32_e32 v4, 1, v0
	v_and_b32_e32 v2, 4, v2
	v_bfe_u32 v3, v0, 2, 2
	v_and_b32_e32 v13, 24, v4
	v_or3_b32 v2, v2, v3, v13
	v_lshlrev_b32_e32 v3, 4, v0
	v_or_b32_e32 v10, 0x2000, v3
	v_lshrrev_b32_e32 v4, 7, v10
	s_movk_i32 s0, 0x60
	v_and_or_b32 v5, v4, s0, v2
	v_bfe_u32 v14, v0, 2, 4
	s_movk_i32 s0, 0x70
	v_and_or_b32 v4, v4, s0, v14
	s_lshr_b32 s0, s3, 29
	s_add_i32 s0, s2, s0
	s_lshr_b32 s5, s1, 6
	s_ashr_i32 s6, s0, 3
	s_and_b32 s0, s0, -8
	s_lshr_b32 s4, s1, 8
	s_lshl_b32 s30, s5, 10
	s_sub_i32 s0, s2, s0
	s_cmp_lt_i32 s0, 0
	s_movk_i32 s31, 0x159
	s_cselect_b32 s7, s31, 0x158
	s_mul_i32 s0, s0, s7
	s_add_i32 s0, s0, s6
	s_mul_hi_i32 s6, s0, 0x2fa0be83
	s_lshr_b32 s7, s6, 31
	s_ashr_i32 s6, s6, 7
	s_add_i32 s6, s6, s7
	s_lshl_b32 s7, s6, 3
	s_mulk_i32 s6, 0x2b0
	s_sub_i32 s6, s0, s6
	s_bfe_u32 s0, s6, 0x3001c
	s_add_i32 s12, s6, s0
	s_sext_i32_i16 s0, s12
	s_and_b32 s12, s12, 0xfff8
	s_sub_i32 s6, s6, s12
	s_sext_i32_i16 s6, s6
	v_and_b32_e32 v6, 32, v0
	s_lshr_b32 s0, s0, 3
	s_add_i32 s22, s7, s6
	v_bitop3_b32 v11, v3, v6, 48 bitop3:0x6c
	v_and_b32_e32 v12, 64, v0
	s_ashr_i32 s23, s22, 31
	s_bfe_i64 s[12:13], s[0:1], 0x100000
	v_or_b32_e32 v3, v11, v12
	s_lshl_b64 s[6:7], s[22:23], 21
	s_lshl_b64 s[12:13], s[12:13], 21
	v_lshl_or_b32 v132, v4, 13, v3
	v_lshrrev_b32_e32 v4, 3, v0
	s_add_u32 s26, s60, s12
	v_and_or_b32 v2, v4, 32, v2
	s_addc_u32 s27, s61, s13
	s_add_i32 s23, s30, 0
	v_lshl_or_b32 v134, v2, 13, v3
	s_add_i32 m0, s23, 0x10000
	v_lshl_or_b32 v130, v5, 13, v3
	global_load_lds_dwordx4 v134, s[26:27]
	s_add_i32 m0, s23, 0x12000
	s_add_u32 s12, s26, 0x100000
	global_load_lds_dwordx4 v130, s[26:27]
	s_addc_u32 s13, s27, 0
	s_add_i32 m0, s23, 0x14000
	v_and_or_b32 v2, v4, 48, v14
	global_load_lds_dwordx4 v134, s[12:13]
	s_add_i32 m0, s23, 0x16000
	s_add_u32 s24, s8, s6
	s_addc_u32 s25, s9, s7
	s_add_i32 s33, s23, 0x2000
	v_lshl_or_b32 v136, v2, 13, v3
	global_load_lds_dwordx4 v130, s[12:13]
	s_mov_b32 m0, s23
	s_add_u32 s6, s24, 0x100000
	global_load_lds_dwordx4 v136, s[24:25]
	s_mov_b32 m0, s33
	s_addc_u32 s7, s25, 0
	s_add_i32 s36, s23, 0x4000
	global_load_lds_dwordx4 v132, s[24:25]
	s_mov_b32 m0, s36
	s_add_i32 s37, s23, 0x6000
	global_load_lds_dwordx4 v136, s[6:7]
	s_mov_b32 m0, s37
	v_mov_b32_e32 v135, 0
	global_load_lds_dwordx4 v132, s[6:7]
	v_mov_b32_e32 v131, v135
	v_mov_b32_e32 v137, v135
	v_mov_b32_e32 v133, v135
	s_cmp_eq_u32 s4, 1
	s_mov_b32 s38, 0
	v_lshl_add_u64 v[8:9], s[26:27], 0, v[134:135]
	v_lshl_add_u64 v[6:7], s[26:27], 0, v[130:131]
	v_lshl_add_u64 v[2:3], s[24:25], 0, v[136:137]
	s_cselect_b64 s[6:7], -1, 0
	s_cmp_lg_u32 s4, 1
	v_lshl_add_u64 v[4:5], s[24:25], 0, v[132:133]
	s_cbranch_scc1 .LBB0_902
	s_barrier
	s_setprio 3

; #define PG8_STAGE(bufoff, gbase, voff) do { _Pragma("unroll") for (int _i = 0; _i < 2; ++_i) \
;         __builtin_amdgcn_global_load_lds((const unsigned*)((const char*)(gbase) + (voff)[_i]), (PG8_LAS unsigned*)(lds + (bufoff) + ldsw + _i * 8192), 16, 0, 0); } while (0)
; #define PG8_BAR __builtin_amdgcn_s_barrier()
;     __device__ __forceinline__ bool next(int i, Unit& u) const { if (i != 0) return false; u.pm = pm; u.pn = pn; return true; }
; template <class Epi, class Sched, bool ALIGN_EPI = false, bool SP2 = false>
; __device__ __forceinline__ void gemm_phase(PG8_LAS unsigned char* lds, const Gemm g, const Sched& S, const Epi& E) {
;     ...
;     for (int i = 0; i < 2; ++i) { int R, C; stage_rc(tid * 16 + i * 8192, R, C); const int Rb = Epi::PERM ? ((R & ~31) + perm32(R & 31)) : R;
;         voffA[i] = (unsigned)(R * g.lda + C) * 2u; voffB[i] = (unsigned)(Rb * g.ldb + C) * 2u; }
;     const size_t kstep = (size_t)(BK * 2);
;     const size_t hstepA = (size_t)HALF * g.lda * 2, hstepB = (size_t)HALF * g.ldb * 2;
;     const size_t tstepA = 2 * hstepA, tstepB = 2 * hstepB;
;     const unsigned ldsw = (unsigned)wid * 1024u;
;     const int aoff = lds_byte(wr * 64 + fr, fq * 8), boff = lds_byte(wc * 32 + fr, fq * 8);
;     ...
;     Unit cur, nxt; int ui = 0;
;     if (!S.next(0, cur)) return;
;     f32x4 acc[2][2][4][2];
; #pragma unroll
;     for (int a = 0; a < 2; ++a)
; #pragma unroll
;         for (int b = 0; b < 2; ++b)
; #pragma unroll
;             for (int m = 0; m < 4; ++m)
; #pragma unroll
;                 for (int n = 0; n < 2; ++n) acc[a][b][m][n] = (f32x4){0.f, 0.f, 0.f, 0.f};
;     bf16x8 At[4][2], B0[2][2], B1[2][2];
;     const char* cA = PG8_ABASE(cur); const char* cB = (const char*)g.Bt + (size_t)cur.pn * tstepB;
;     S.a_ready(cur);
;     if constexpr (SP2) {
;         PG8_STAGE(PG8_SB(0, 0), cB, voffB); PG8_STAGE(PG8_SB(0, 1), cB + hstepB, voffB); PG8_STAGE(PG8_SA(0, 0), cA, voffA); PG8_STAGE(PG8_SA(0, 1), cA + hstepA, voffA);
;         if (wr == 1) PG8_BAR;
.LBB0_970:
	s_cmp_lt_i32 s70, 10
	s_cselect_b64 s[0:1], -1, 0
	s_cmp_gt_i32 s71, 9
	s_cselect_b64 s[4:5], -1, 0
	s_and_b64 s[0:1], s[0:1], s[4:5]
	s_andn2_b64 vcc, exec, s[0:1]
	s_cbranch_vccnz .LBB0_1059
	s_andn2_b64 vcc, exec, s[34:35]
	s_cbranch_vccnz .LBB0_1059
	v_lshlrev_b32_e32 v2, 4, v0
	v_and_b32_e32 v3, 32, v0
	v_bitop3_b32 v6, v2, v3, 48 bitop3:0x6c
	v_lshrrev_b32_e32 v3, 1, v0
	v_lshrrev_b32_e32 v5, 5, v0
	v_and_b32_e32 v3, 24, v3
	v_and_b32_e32 v5, 4, v5
	v_bfe_u32 v8, v0, 2, 2
	v_bfe_u32 v4, v0, 2, 4
	v_and_b32_e32 v7, 64, v0
	v_or3_b32 v3, v5, v8, v3
	v_lshrrev_b32_e32 v5, 3, v0
	s_lshl_b32 s0, s2, 1
	v_or_b32_e32 v2, v6, v7
	v_and_or_b32 v8, v5, 48, v4
	v_and_or_b32 v5, v5, 32, v3
	s_and_b32 s34, s0, 12
	s_lshl_b32 s0, s2, 3
	v_lshrrev_b32_e32 v2, 1, v2
	v_mul_u32_u24_e32 v5, 0x2b00, v5
	s_and_b32 s0, s0, 8
	s_ashr_i32 s1, s2, 5
	v_readfirstlane_b32 s40, v0
	v_or_b32_e32 v5, v5, v2
	s_bfe_u32 s35, s2, 0x20003
	s_add_i32 s6, s0, s1
	s_lshr_b32 s41, s40, 6
	v_lshlrev_b32_e32 v174, 1, v5
	v_bfe_u32 v5, v0, 3, 25
	s_or_b32 s36, s34, s35
	s_lshr_b32 s3, s40, 8
	v_or_b32_e32 v5, 64, v5
	s_movk_i32 s0, 0x70
	s_lshl_b32 s28, s41, 10
	s_ashr_i32 s7, s6, 31
	s_mul_i32 s13, s6, 0x560000
	v_mul_u32_u24_e32 v8, 0x2b00, v8
	v_and_or_b32 v4, v5, s0, v4
	s_movk_i32 s0, 0x60
	s_mul_hi_i32 s12, s6, 0x560000
	s_add_u32 s10, s10, s13
	v_or_b32_e32 v9, v2, v8
	v_and_or_b32 v3, v5, s0, v3
	s_addc_u32 s11, s11, s12
	s_add_i32 s42, s28, 0
	v_lshlrev_b32_e32 v172, 1, v9
	v_mul_u32_u24_e32 v9, 0x2b00, v4
	v_mul_u32_u24_e32 v3, 0x2b00, v3
	s_add_i32 m0, s42, 0x10000
	v_or_b32_e32 v4, v9, v2
	v_or_b32_e32 v2, v3, v2
	global_load_lds_dwordx4 v174, s[10:11]
	s_add_i32 m0, s42, 0x12000
	v_lshlrev_b32_e32 v178, 1, v2
	s_add_u32 s4, s10, 0x2b0000
	global_load_lds_dwordx4 v178, s[10:11]
	s_addc_u32 s5, s11, 0
	s_add_i32 m0, s42, 0x14000
	s_mul_i32 s0, s36, 0x560000
	global_load_lds_dwordx4 v174, s[4:5]
	s_add_i32 m0, s42, 0x16000
	v_readlane_b32 s14, v244, 11
	v_readlane_b32 s15, v244, 12
	s_add_u32 s0, s14, s0
	s_addc_u32 s1, s15, 0
	s_add_i32 s54, s42, 0x2000
	global_load_lds_dwordx4 v178, s[4:5]
	s_mov_b32 m0, s42
	s_add_u32 s14, s0, 0x2b0000
	v_lshlrev_b32_e32 v176, 1, v4
	global_load_lds_dwordx4 v172, s[0:1]
	s_mov_b32 m0, s54
	s_addc_u32 s15, s1, 0
	s_add_i32 s55, s42, 0x4000
	global_load_lds_dwordx4 v176, s[0:1]
	s_mov_b32 m0, s55
	s_add_i32 s56, s42, 0x6000
	global_load_lds_dwordx4 v172, s[14:15]
	s_mov_b32 m0, s56
	v_mov_b32_e32 v175, 0
	global_load_lds_dwordx4 v176, s[14:15]
	v_mov_b32_e32 v179, v175
	v_mov_b32_e32 v173, v175
	v_mov_b32_e32 v177, v175
	v_lshl_add_u64 v[190:191], s[10:11], 0, v[174:175]
	v_lshl_add_u64 v[188:189], s[10:11], 0, v[178:179]
	v_lshl_add_u64 v[4:5], s[0:1], 0, v[172:173]
	s_cmp_lg_u32 s3, 1
	v_lshl_add_u64 v[2:3], s[0:1], 0, v[176:177]
	s_cbranch_scc1 .LBB0_974
	s_barrier
	s_setprio 3

;     __device__ __forceinline__ void fused(f32x4 (&acc)[2][2][4][2], const Unit& u, int wr, int wc, int fr, int fq, PG8_LAS unsigned char* lds, int wid, int lane) const {
;     ...
;         asm volatile("s_waitcnt lgkmcnt(0)" ::: "memory"); __builtin_amdgcn_s_barrier(); asm volatile("" ::: "memory");
;         f32x4 gv[2][2];
; #pragma unroll
;         for (int bj = 0; bj < 2; ++bj)
; #pragma unroll
;             for (int n = 0; n < 2; ++n) gv[bj][n] = *(const f32x4*)(gain + col0 + bj * HALF + 4 * n);
; #pragma unroll
;         for (int ai = 0; ai < 2; ++ai)
; #pragma unroll
;             for (int m = 0; m < 4; ++m) { const int rl = ai * HALF + wr * 64 + m * 16 + fr; const float rs = Sx[rl]; const size_t ro = (size_t)(u.pm * BM + rl) * D + col0;
; #pragma unroll
;                 for (int bj = 0; bj < 2; ++bj) { *(f32x4*)(O + ro + bj * HALF) = acc[ai][bj][m][0] * rs * gv[bj][0]; *(f32x4*)(O + ro + bj * HALF + 4) = acc[ai][bj][m][1] * rs * gv[bj][1]; } }
.LBB0_1015:
	s_or_b64 exec, exec, s[16:17]
	v_lshl_or_b32 v207, v203, 3, s37
	v_or_b32_e32 v2, s38, v207
	v_ashrrev_i32_e32 v3, 31, v2
	v_lshlrev_b64 v[148:149], 2, v[2:3]
	s_waitcnt lgkmcnt(0)
	s_barrier
	v_lshl_add_u64 v[2:3], s[48:49], 0, v[148:149]
	global_load_dwordx4 v[144:147], v[2:3], off
	global_load_dwordx4 v[140:143], v[2:3], off offset:16
	global_load_dwordx4 v[136:139], v[2:3], off offset:512
	s_waitcnt lgkmcnt(0)
	global_load_dwordx4 v[132:135], v[2:3], off offset:528
	v_lshl_add_u32 v1, v208, 2, 0
	v_add_u32_e32 v1, 0x1000, v1
	ds_read2_b32 v[156:157], v1 offset1:16
	ds_read2_b32 v[158:159], v1 offset0:32 offset1:48
	v_add_u32_e32 v2, s39, v208
	v_mov_b32_e32 v3, 0
	v_add_u32_e32 v154, 32, v2
	v_mov_b32_e32 v155, v3
	v_lshlrev_b64 v[150:151], 14, v[2:3]
	v_add_u32_e32 v152, 16, v2
	v_mov_b32_e32 v153, v3
	v_lshlrev_b64 v[154:155], 14, v[154:155]
	v_lshl_add_u64 v[150:151], s[50:51], 0, v[150:151]
	v_lshlrev_b64 v[152:153], 14, v[152:153]
	v_lshl_add_u64 v[154:155], s[50:51], 0, v[154:155]
	s_waitcnt lgkmcnt(0)
	v_pk_mul_f32 v[128:129], v[128:129], v[156:157] op_sel_hi:[1,0]
	v_pk_mul_f32 v[130:131], v[130:131], v[156:157] op_sel_hi:[1,0]
	v_pk_mul_f32 v[124:125], v[124:125], v[156:157] op_sel_hi:[1,0]
	v_pk_mul_f32 v[126:127], v[126:127], v[156:157] op_sel_hi:[1,0]
	v_pk_mul_f32 v[120:121], v[120:121], v[156:157] op_sel_hi:[1,0]
	v_pk_mul_f32 v[122:123], v[122:123], v[156:157] op_sel_hi:[1,0]
	v_pk_mul_f32 v[116:117], v[116:117], v[156:157] op_sel_hi:[1,0]
	v_pk_mul_f32 v[118:119], v[118:119], v[156:157] op_sel_hi:[1,0]
	v_mov_b32_e32 v156, v157
	v_pk_mul_f32 v[84:85], v[84:85], v[158:159] op_sel_hi:[1,0]
	v_pk_mul_f32 v[86:87], v[86:87], v[158:159] op_sel_hi:[1,0]
	v_lshl_add_u64 v[152:153], s[50:51], 0, v[152:153]
	v_lshl_add_u64 v[150:151], v[150:151], 0, v[148:149]
	v_lshl_add_u64 v[154:155], v[154:155], 0, v[148:149]
	v_pk_mul_f32 v[160:161], v[112:113], v[158:159] op_sel_hi:[1,0]
	v_pk_mul_f32 v[162:163], v[114:115], v[158:159] op_sel_hi:[1,0]
	v_pk_mul_f32 v[164:165], v[108:109], v[158:159] op_sel_hi:[1,0]
	v_pk_mul_f32 v[166:167], v[110:111], v[158:159] op_sel_hi:[1,0]
	v_pk_mul_f32 v[168:169], v[104:105], v[158:159] op_sel_hi:[1,0]
	v_pk_mul_f32 v[170:171], v[106:107], v[158:159] op_sel_hi:[1,0]
	v_pk_mul_f32 v[104:105], v[100:101], v[156:157] op_sel_hi:[1,0]
	v_pk_mul_f32 v[106:107], v[102:103], v[156:157] op_sel_hi:[1,0]
	v_pk_mul_f32 v[108:109], v[96:97], v[156:157] op_sel_hi:[1,0]
	v_pk_mul_f32 v[110:111], v[98:99], v[156:157] op_sel_hi:[1,0]
	v_pk_mul_f32 v[112:113], v[92:93], v[156:157] op_sel_hi:[1,0]
	v_pk_mul_f32 v[114:115], v[94:95], v[156:157] op_sel_hi:[1,0]
	v_pk_mul_f32 v[208:209], v[88:89], v[156:157] op_sel_hi:[1,0]
	v_pk_mul_f32 v[156:157], v[90:91], v[156:157] op_sel_hi:[1,0]
	v_lshl_add_u64 v[152:153], v[152:153], 0, v[148:149]
	v_readfirstlane_b32 s56, v0
	s_lshr_b32 s57, s56, 6
	s_lshl_b32 s40, s57, 10
	s_add_i32 s58, s40, 0
	s_add_i32 m0, s58, 0x10000
	s_or_b32 s20, s36, 16
	s_lshr_b32 s18, s56, 8
	s_mul_i32 s16, s20, 0x560000
	s_waitcnt vmcnt(0)
	v_pk_mul_f32 v[90:91], v[146:147], v[130:131]
	v_pk_mul_f32 v[88:89], v[144:145], v[128:129]
	v_pk_mul_f32 v[94:95], v[142:143], v[126:127]
	v_pk_mul_f32 v[86:87], v[134:135], v[86:87]
	v_pk_mul_f32 v[84:85], v[132:133], v[84:85]
	v_pk_mul_f32 v[92:93], v[140:141], v[124:125]
	v_pk_mul_f32 v[98:99], v[138:139], v[122:123]
	v_pk_mul_f32 v[96:97], v[136:137], v[120:121]
	v_pk_mul_f32 v[102:103], v[134:135], v[118:119]
	v_pk_mul_f32 v[100:101], v[132:133], v[116:117]
	v_pk_mul_f32 v[106:107], v[146:147], v[106:107]
	v_pk_mul_f32 v[104:105], v[144:145], v[104:105]
	v_pk_mul_f32 v[110:111], v[142:143], v[110:111]
	v_pk_mul_f32 v[108:109], v[140:141], v[108:109]
	v_pk_mul_f32 v[114:115], v[138:139], v[114:115]
	v_pk_mul_f32 v[112:113], v[136:137], v[112:113]
	v_pk_mul_f32 v[118:119], v[134:135], v[156:157]
	v_pk_mul_f32 v[116:117], v[132:133], v[208:209]
	v_pk_mul_f32 v[122:123], v[146:147], v[162:163]
	v_pk_mul_f32 v[120:121], v[144:145], v[160:161]
	v_pk_mul_f32 v[126:127], v[142:143], v[166:167]
	v_pk_mul_f32 v[124:125], v[140:141], v[164:165]
	v_pk_mul_f32 v[130:131], v[138:139], v[170:171]
	v_pk_mul_f32 v[128:129], v[136:137], v[168:169]
	global_store_dwordx4 v[150:151], v[88:91], off
	global_store_dwordx4 v[150:151], v[92:95], off offset:16
	global_store_dwordx4 v[150:151], v[96:99], off offset:512
	global_store_dwordx4 v[150:151], v[100:103], off offset:528
	global_store_dwordx4 v[152:153], v[104:107], off
	global_store_dwordx4 v[152:153], v[108:111], off offset:16
	global_store_dwordx4 v[152:153], v[112:115], off offset:512
	global_store_dwordx4 v[152:153], v[116:119], off offset:528
	global_store_dwordx4 v[154:155], v[120:123], off
	global_store_dwordx4 v[154:155], v[124:127], off offset:16
	global_store_dwordx4 v[154:155], v[128:131], off offset:512
	global_store_dwordx4 v[154:155], v[84:87], off offset:528
	s_nop 1
	v_add_u32_e32 v84, 48, v2
	v_mov_b32_e32 v85, v3
	v_mov_b32_e32 v86, v159
	v_lshlrev_b64 v[84:85], 14, v[84:85]
	v_lshl_add_u64 v[84:85], s[50:51], 0, v[84:85]
	v_pk_mul_f32 v[72:73], v[72:73], v[86:87] op_sel_hi:[1,0]
	v_pk_mul_f32 v[74:75], v[74:75], v[86:87] op_sel_hi:[1,0]
	v_lshl_add_u64 v[84:85], v[84:85], 0, v[148:149]
	v_pk_mul_f32 v[74:75], v[138:139], v[74:75]
	v_pk_mul_f32 v[72:73], v[136:137], v[72:73]
	global_store_dwordx4 v[84:85], v[72:75], off offset:512
	ds_read2_b32 v[72:73], v1 offset0:128 offset1:144
	v_pk_mul_f32 v[68:69], v[68:69], v[86:87] op_sel_hi:[1,0]
	v_pk_mul_f32 v[70:71], v[70:71], v[86:87] op_sel_hi:[1,0]
	v_pk_mul_f32 v[68:69], v[132:133], v[68:69]
	v_pk_mul_f32 v[70:71], v[134:135], v[70:71]
	global_store_dwordx4 v[84:85], v[68:71], off offset:528
	s_waitcnt lgkmcnt(0)
; #define PG8_STAGE(bufoff, gbase, voff) do { _Pragma("unroll") for (int _i = 0; _i < 2; ++_i) \
;         __builtin_amdgcn_global_load_lds((const unsigned*)((const char*)(gbase) + (voff)[_i]), (PG8_LAS unsigned*)(lds + (bufoff) + ldsw + _i * 8192), 16, 0, 0); } while (0)
; #define PG8_BAR __builtin_amdgcn_s_barrier()
; template <class Epi, class Sched, bool ALIGN_EPI = false, bool SP2 = false>
; __device__ __forceinline__ void gemm_phase(PG8_LAS unsigned char* lds, const Gemm g, const Sched& S, const Epi& E) {
;     ...
;     const char* cA = PG8_ABASE(cur); const char* cB = (const char*)g.Bt + (size_t)cur.pn * tstepB;
;     S.a_ready(cur);
;     if constexpr (SP2) {
;         PG8_STAGE(PG8_SB(0, 0), cB, voffB); PG8_STAGE(PG8_SB(0, 1), cB + hstepB, voffB); PG8_STAGE(PG8_SA(0, 0), cA, voffA); PG8_STAGE(PG8_SA(0, 1), cA + hstepA, voffA);
;         if (wr == 1) PG8_BAR;
;     __device__ __forceinline__ void fused(f32x4 (&acc)[2][2][4][2], const Unit& u, int wr, int wc, int fr, int fq, PG8_LAS unsigned char* lds, int wid, int lane) const {
;     ...
;         for (int ai = 0; ai < 2; ++ai)
; #pragma unroll
;             for (int m = 0; m < 4; ++m) { const int rl = ai * HALF + wr * 64 + m * 16 + fr; const float rs = Sx[rl]; const size_t ro = (size_t)(u.pm * BM + rl) * D + col0;
; #pragma unroll
;                 for (int bj = 0; bj < 2; ++bj) { *(f32x4*)(O + ro + bj * HALF) = acc[ai][bj][m][0] * rs * gv[bj][0]; *(f32x4*)(O + ro + bj * HALF + 4) = acc[ai][bj][m][1] * rs * gv[bj][1]; } }
	v_pk_mul_f32 v[52:53], v[52:53], v[72:73] op_sel_hi:[1,0]
	v_pk_mul_f32 v[54:55], v[54:55], v[72:73] op_sel_hi:[1,0]
	v_add_u32_e32 v68, 0x80, v2
	v_mov_b32_e32 v69, v3
	v_lshlrev_b64 v[68:69], 14, v[68:69]
	v_lshl_add_u64 v[68:69], s[50:51], 0, v[68:69]
	v_lshl_add_u64 v[68:69], v[68:69], 0, v[148:149]
	v_pk_mul_f32 v[54:55], v[134:135], v[54:55]
	v_pk_mul_f32 v[52:53], v[132:133], v[52:53]
	global_store_dwordx4 v[68:69], v[52:55], off offset:528
	v_pk_mul_f32 v[80:81], v[80:81], v[86:87] op_sel_hi:[1,0]
	v_pk_mul_f32 v[82:83], v[82:83], v[86:87] op_sel_hi:[1,0]
	v_add_u32_e32 v52, 0x90, v2
	v_mov_b32_e32 v53, v3
	v_mov_b32_e32 v54, v73
	v_lshlrev_b64 v[52:53], 14, v[52:53]
	v_lshl_add_u64 v[52:53], s[50:51], 0, v[52:53]
	v_pk_mul_f32 v[40:41], v[40:41], v[54:55] op_sel_hi:[1,0]
	v_pk_mul_f32 v[42:43], v[42:43], v[54:55] op_sel_hi:[1,0]
	v_lshl_add_u64 v[52:53], v[52:53], 0, v[148:149]
	v_pk_mul_f32 v[42:43], v[138:139], v[42:43]
	v_pk_mul_f32 v[40:41], v[136:137], v[40:41]
	global_store_dwordx4 v[52:53], v[40:43], off offset:512
	ds_read2_b32 v[40:41], v1 offset0:160 offset1:176
	v_pk_mul_f32 v[36:37], v[36:37], v[54:55] op_sel_hi:[1,0]
	v_pk_mul_f32 v[38:39], v[38:39], v[54:55] op_sel_hi:[1,0]
	v_pk_mul_f32 v[36:37], v[132:133], v[36:37]
	v_pk_mul_f32 v[38:39], v[134:135], v[38:39]
	global_store_dwordx4 v[52:53], v[36:39], off offset:528
	s_waitcnt lgkmcnt(0)
	v_pk_mul_f32 v[20:21], v[20:21], v[40:41] op_sel_hi:[1,0]
	v_pk_mul_f32 v[22:23], v[22:23], v[40:41] op_sel_hi:[1,0]
	v_add_u32_e32 v36, 0xa0, v2
	v_mov_b32_e32 v37, v3
	v_lshlrev_b64 v[36:37], 14, v[36:37]
	v_lshl_add_u64 v[36:37], s[50:51], 0, v[36:37]
	v_lshl_add_u64 v[36:37], v[36:37], 0, v[148:149]
	v_pk_mul_f32 v[22:23], v[134:135], v[22:23]
	v_pk_mul_f32 v[20:21], v[132:133], v[20:21]
	v_add_u32_e32 v2, 0xb0, v2
	global_store_dwordx4 v[36:37], v[20:23], off offset:528
	v_pk_mul_f32 v[76:77], v[76:77], v[86:87] op_sel_hi:[1,0]
	v_pk_mul_f32 v[78:79], v[78:79], v[86:87] op_sel_hi:[1,0]
	v_mov_b32_e32 v20, v41
	v_lshlrev_b64 v[22:23], 14, v[2:3]
	v_pk_mul_f32 v[64:65], v[64:65], v[72:73] op_sel_hi:[1,0]
	v_pk_mul_f32 v[66:67], v[66:67], v[72:73] op_sel_hi:[1,0]
	v_pk_mul_f32 v[60:61], v[60:61], v[72:73] op_sel_hi:[1,0]
	v_pk_mul_f32 v[62:63], v[62:63], v[72:73] op_sel_hi:[1,0]
	v_pk_mul_f32 v[56:57], v[56:57], v[72:73] op_sel_hi:[1,0]
	v_pk_mul_f32 v[58:59], v[58:59], v[72:73] op_sel_hi:[1,0]
	v_pk_mul_f32 v[48:49], v[48:49], v[54:55] op_sel_hi:[1,0]
	v_pk_mul_f32 v[50:51], v[50:51], v[54:55] op_sel_hi:[1,0]
	v_pk_mul_f32 v[44:45], v[44:45], v[54:55] op_sel_hi:[1,0]
	v_pk_mul_f32 v[46:47], v[46:47], v[54:55] op_sel_hi:[1,0]
	v_pk_mul_f32 v[32:33], v[32:33], v[40:41] op_sel_hi:[1,0]
	v_pk_mul_f32 v[34:35], v[34:35], v[40:41] op_sel_hi:[1,0]
	v_pk_mul_f32 v[28:29], v[28:29], v[40:41] op_sel_hi:[1,0]
	v_pk_mul_f32 v[30:31], v[30:31], v[40:41] op_sel_hi:[1,0]
	v_pk_mul_f32 v[24:25], v[24:25], v[40:41] op_sel_hi:[1,0]
	v_pk_mul_f32 v[26:27], v[26:27], v[40:41] op_sel_hi:[1,0]
	v_pk_mul_f32 v[16:17], v[16:17], v[20:21] op_sel_hi:[1,0]
	v_pk_mul_f32 v[18:19], v[18:19], v[20:21] op_sel_hi:[1,0]
	v_lshl_add_u64 v[22:23], s[50:51], 0, v[22:23]
	v_pk_mul_f32 v[12:13], v[12:13], v[20:21] op_sel_hi:[1,0]
	v_pk_mul_f32 v[14:15], v[14:15], v[20:21] op_sel_hi:[1,0]
	v_pk_mul_f32 v[8:9], v[8:9], v[20:21] op_sel_hi:[1,0]
	v_pk_mul_f32 v[10:11], v[10:11], v[20:21] op_sel_hi:[1,0]
	v_pk_mul_f32 v[4:5], v[4:5], v[20:21] op_sel_hi:[1,0]
	v_pk_mul_f32 v[6:7], v[6:7], v[20:21] op_sel_hi:[1,0]
	v_pk_mul_f32 v[82:83], v[146:147], v[82:83]
	v_pk_mul_f32 v[80:81], v[144:145], v[80:81]
	v_pk_mul_f32 v[78:79], v[142:143], v[78:79]
	v_pk_mul_f32 v[76:77], v[140:141], v[76:77]
	v_pk_mul_f32 v[66:67], v[146:147], v[66:67]
	v_pk_mul_f32 v[64:65], v[144:145], v[64:65]
	v_pk_mul_f32 v[62:63], v[142:143], v[62:63]
	v_pk_mul_f32 v[60:61], v[140:141], v[60:61]
	v_pk_mul_f32 v[58:59], v[138:139], v[58:59]
	v_pk_mul_f32 v[56:57], v[136:137], v[56:57]
	v_pk_mul_f32 v[50:51], v[146:147], v[50:51]
	v_pk_mul_f32 v[48:49], v[144:145], v[48:49]
	v_pk_mul_f32 v[46:47], v[142:143], v[46:47]
	v_pk_mul_f32 v[44:45], v[140:141], v[44:45]
	v_pk_mul_f32 v[34:35], v[146:147], v[34:35]
	v_pk_mul_f32 v[32:33], v[144:145], v[32:33]
	v_pk_mul_f32 v[30:31], v[142:143], v[30:31]
	v_pk_mul_f32 v[28:29], v[140:141], v[28:29]
	v_pk_mul_f32 v[26:27], v[138:139], v[26:27]
	v_pk_mul_f32 v[24:25], v[136:137], v[24:25]
	v_pk_mul_f32 v[18:19], v[146:147], v[18:19]
	v_pk_mul_f32 v[16:17], v[144:145], v[16:17]
	v_lshl_add_u64 v[22:23], v[22:23], 0, v[148:149]
	v_pk_mul_f32 v[14:15], v[142:143], v[14:15]
	v_pk_mul_f32 v[12:13], v[140:141], v[12:13]
	v_pk_mul_f32 v[10:11], v[138:139], v[10:11]
	v_pk_mul_f32 v[8:9], v[136:137], v[8:9]
	v_pk_mul_f32 v[6:7], v[134:135], v[6:7]
	v_pk_mul_f32 v[4:5], v[132:133], v[4:5]
	global_store_dwordx4 v[84:85], v[80:83], off
	global_store_dwordx4 v[84:85], v[76:79], off offset:16
	global_store_dwordx4 v[68:69], v[64:67], off
	global_store_dwordx4 v[68:69], v[60:63], off offset:16
	global_store_dwordx4 v[68:69], v[56:59], off offset:512
	global_store_dwordx4 v[52:53], v[48:51], off
	global_store_dwordx4 v[52:53], v[44:47], off offset:16
	global_store_dwordx4 v[36:37], v[32:35], off
	global_store_dwordx4 v[36:37], v[28:31], off offset:16
	global_store_dwordx4 v[36:37], v[24:27], off offset:512
	global_store_dwordx4 v[22:23], v[16:19], off
	global_store_dwordx4 v[22:23], v[12:15], off offset:16
	global_store_dwordx4 v[22:23], v[8:11], off offset:512
	global_store_dwordx4 v[22:23], v[4:7], off offset:528
	s_barrier
	global_load_lds_dwordx4 v[190:191], off
	s_add_i32 m0, s58, 0x12000
	s_nop 0
	global_load_lds_dwordx4 v[188:189], off
	s_add_i32 m0, s58, 0x14000
	s_nop 0
	global_load_lds_dwordx4 v[198:199], off
	s_add_i32 m0, s58, 0x16000
	s_add_u32 s16, s24, s16
	s_addc_u32 s17, s25, 0
	s_add_i32 s60, s58, 0x2000
	global_load_lds_dwordx4 v[196:197], off
	v_lshl_add_u64 v[4:5], s[16:17], 0, v[172:173]
	s_mov_b32 m0, s58
	s_add_u32 s22, s16, 0x2b0000
	global_load_lds_dwordx4 v[4:5], off
	v_lshl_add_u64 v[0:1], s[16:17], 0, v[176:177]
	s_mov_b32 m0, s60
	s_addc_u32 s23, s17, 0
	s_add_i32 s61, s58, 0x4000
	global_load_lds_dwordx4 v[0:1], off
	v_lshl_add_u64 v[6:7], s[22:23], 0, v[172:173]
	s_mov_b32 m0, s61
	s_add_i32 s62, s58, 0x6000
	global_load_lds_dwordx4 v[6:7], off
	v_lshl_add_u64 v[6:7], s[22:23], 0, v[176:177]
	s_mov_b32 m0, s62
	s_cmp_lg_u32 s18, 1
	global_load_lds_dwordx4 v[6:7], off
	s_cbranch_scc1 .LBB0_1017
	s_barrier
	s_setprio 3
